# v050 plus 20 s_nop 0 removed before LDS-DMA loads by issuing the m0 write ahead of the address VALU op
# baseline (speedup 1.0000x reference)
; #define PG8_STAGE(bufoff, gbase, voff) do { _Pragma("unroll") for (int _i = 0; _i < 2; ++_i) \
;         __builtin_amdgcn_global_load_lds((const unsigned*)((const char*)(gbase) + (voff)[_i]), (PG8_LAS unsigned*)(lds + (bufoff) + ldsw + _i * 8192), 16, 0, 0); } while (0)
; #define PG8_LDA(dst, b, h) do { _Pragma("unroll") for (int m = 0; m < 4; ++m) _Pragma("unroll") for (int k = 0; k < 2; ++k) dst[m][k] = *(const PG8_LAS bf16x8*)(lds + PG8_SA(b, h) + aoff + m * 2048 + k * 1024); } while (0)
; #define PG8_LDB(dst, b, h) do { _Pragma("unroll") for (int n = 0; n < 2; ++n) _Pragma("unroll") for (int k = 0; k < 2; ++k) dst[n][k] = *(const PG8_LAS bf16x8*)(lds + PG8_SB(b, h) + boff + n * 2048 + k * 1024); } while (0)
; #define PG8_MMA(ai, bj, At, Bt) do { __builtin_amdgcn_s_setprio(1); _Pragma("unroll") for (int m = 0; m < 4; ++m) _Pragma("unroll") for (int n = 0; n < 2; ++n) _Pragma("unroll") for (int k = 0; k < 2; ++k) \
;         acc[ai][bj][m][n] = __builtin_amdgcn_mfma_f32_16x16x32_bf16(Bt[n][k], At[m][k], acc[ai][bj][m][n], 0, 0, 0); __builtin_amdgcn_s_setprio(0); } while (0)
; #define PG8_WAIT_V(n) asm volatile("s_waitcnt vmcnt(" #n ")" ::: "memory")
; #define PG8_WAIT_L(n) asm volatile("s_waitcnt lgkmcnt(" #n ")" ::: "memory")
; #define PG8_BAR __builtin_amdgcn_s_barrier()
; #define PG8_SCHED __builtin_amdgcn_sched_barrier(0)
; template <class Epi, class Sched, bool ALIGN_EPI = false, bool SP2 = false>
; __device__ __forceinline__ void gemm_phase(PG8_LAS unsigned char* lds, const Gemm g, const Sched& S, const Epi& E) {
;     ...
;         for (int t = 0; t < nt; t += 2) {
;             const bool last = (t == nt - 2);
;             const char* a1 = cA + (size_t)(t + 1) * kstep;
;             const char* a2 = last ? nA : cA + (size_t)(t + 2) * kstep; const char* b2 = last ? nB : cB + (size_t)(t + 2) * kstep;
;             const char* a3 = a2 + kstep; const char* b3 = b2 + kstep;
;             if (last && has_next) S.a_ready(nxt);
;             if constexpr (SP2) {
;             PG8_LDB(B0, 0, 0); PG8_LDB(B1, 0, 1); PG8_SCHED; PG8_LDA(At, 0, 0); PG8_STAGE(PG8_SA(1, 1), a1 + hstep, voffA);
;             PG8_WAIT_V(8); PG8_WAIT_L(0); PG8_BAR; PG8_MMA(0, 0, At, B0); PG8_MMA(0, 1, At, B1); PG8_BAR; PG8_SCHED;
;             PG8_LDA(At, 0, 1); PG8_STAGE(PG8_SB(0, 0), b2, voffB); PG8_STAGE(PG8_SB(0, 1), b2 + hstep, voffB); PG8_STAGE(PG8_SA(0, 0), a2, voffA);
.LBB0_117:
	s_add_u32 s50, s48, 0xfff80080
	s_addc_u32 s51, s49, -1
	s_add_i32 s61, 0, 0x10000
	s_cmp_eq_u32 s58, 28
	s_cselect_b32 s77, s1, s51
	s_cselect_b32 s76, s24, s50
	v_add_u32_e32 v0, s61, v234
	s_cselect_b32 s51, s25, s47
	s_cselect_b32 s50, s38, s39
	s_add_i32 s63, 0, 0x14000
	ds_read_b128 v[124:127], v0
	ds_read_b128 v[128:131], v0 offset:1024
	ds_read_b128 v[132:135], v0 offset:2048
	ds_read_b128 v[140:143], v0 offset:3072
	v_add_u32_e32 v0, s63, v234
	ds_read_b128 v[148:151], v0
	ds_read_b128 v[152:155], v0 offset:1024
	ds_read_b128 v[156:159], v0 offset:2048
	ds_read_b128 v[160:163], v0 offset:3072
	v_lshl_add_u64 v[2:3], s[48:49], 0, v[192:193]
	s_add_i32 m0, s82, 0xc000
	ds_read_b128 v[164:167], v235
	ds_read_b128 v[198:201], v235 offset:1024
	ds_read_b128 v[202:205], v235 offset:2048
	ds_read_b128 v[206:209], v235 offset:3072
	ds_read_b128 v[210:213], v235 offset:4096
	ds_read_b128 v[214:217], v235 offset:5120
	ds_read_b128 v[218:221], v235 offset:6144
	ds_read_b128 v[236:239], v235 offset:7168
	global_load_lds_dwordx4 v[2:3], off
	s_add_i32 m0, s82, 0xe000
	v_lshl_add_u64 v[2:3], s[48:49], 0, v[194:195]
	global_load_lds_dwordx4 v[2:3], off
	s_waitcnt vmcnt(8) lgkmcnt(0)
	s_setprio 1
	s_barrier
	v_mfma_f32_16x16x32_bf16 v[144:147], v[124:127], v[164:167], v[144:147]
	v_mfma_f32_16x16x32_bf16 v[136:139], v[132:135], v[164:167], v[136:139]
	v_mfma_f32_16x16x32_bf16 v[112:115], v[124:127], v[202:205], v[112:115]
	v_mfma_f32_16x16x32_bf16 v[108:111], v[132:135], v[202:205], v[108:111]
	v_mfma_f32_16x16x32_bf16 v[96:99], v[124:127], v[210:213], v[96:99]
	v_mfma_f32_16x16x32_bf16 v[92:95], v[132:135], v[210:213], v[92:95]
	v_mfma_f32_16x16x32_bf16 v[80:83], v[124:127], v[218:221], v[80:83]
	v_mfma_f32_16x16x32_bf16 v[76:79], v[132:135], v[218:221], v[76:79]
	v_mfma_f32_16x16x32_bf16 v[144:147], v[128:131], v[198:201], v[144:147]
	v_mfma_f32_16x16x32_bf16 v[136:139], v[140:143], v[198:201], v[136:139]
	v_mfma_f32_16x16x32_bf16 v[112:115], v[128:131], v[206:209], v[112:115]
	v_mfma_f32_16x16x32_bf16 v[108:111], v[140:143], v[206:209], v[108:111]
	v_mfma_f32_16x16x32_bf16 v[96:99], v[128:131], v[214:217], v[96:99]
	v_mfma_f32_16x16x32_bf16 v[92:95], v[140:143], v[214:217], v[92:95]
	v_mfma_f32_16x16x32_bf16 v[80:83], v[128:131], v[236:239], v[80:83]
	v_mfma_f32_16x16x32_bf16 v[76:79], v[140:143], v[236:239], v[76:79]
	s_setprio 0
	s_setprio 1
	v_mfma_f32_16x16x32_bf16 v[120:123], v[148:151], v[164:167], v[120:123]
	v_mfma_f32_16x16x32_bf16 v[116:119], v[156:159], v[164:167], v[116:119]
	v_mfma_f32_16x16x32_bf16 v[104:107], v[148:151], v[202:205], v[104:107]
	v_mfma_f32_16x16x32_bf16 v[100:103], v[156:159], v[202:205], v[100:103]
	v_mfma_f32_16x16x32_bf16 v[88:91], v[148:151], v[210:213], v[88:91]
	v_mfma_f32_16x16x32_bf16 v[84:87], v[156:159], v[210:213], v[84:87]
	v_mfma_f32_16x16x32_bf16 v[72:75], v[148:151], v[218:221], v[72:75]
	v_mfma_f32_16x16x32_bf16 v[68:71], v[156:159], v[218:221], v[68:71]
	v_mfma_f32_16x16x32_bf16 v[120:123], v[152:155], v[198:201], v[120:123]
	v_mfma_f32_16x16x32_bf16 v[116:119], v[160:163], v[198:201], v[116:119]
	v_mfma_f32_16x16x32_bf16 v[104:107], v[152:155], v[206:209], v[104:107]
	v_mfma_f32_16x16x32_bf16 v[100:103], v[160:163], v[206:209], v[100:103]
	v_mfma_f32_16x16x32_bf16 v[88:91], v[152:155], v[214:217], v[88:91]
	v_mfma_f32_16x16x32_bf16 v[84:87], v[160:163], v[214:217], v[84:87]
	v_mfma_f32_16x16x32_bf16 v[72:75], v[152:155], v[236:239], v[72:75]
	v_mfma_f32_16x16x32_bf16 v[68:71], v[160:163], v[236:239], v[68:71]
	s_setprio 0
	s_barrier
	s_add_i32 s61, s61, s73
	v_lshl_add_u64 v[168:169], s[50:51], 0, v[182:183]
	s_mov_b32 m0, s61
	ds_read_b128 v[164:167], v235 offset:16384
	ds_read_b128 v[198:201], v235 offset:17408
	ds_read_b128 v[202:205], v235 offset:18432
	ds_read_b128 v[206:209], v235 offset:19456
	ds_read_b128 v[210:213], v235 offset:20480
	ds_read_b128 v[214:217], v235 offset:21504
	ds_read_b128 v[218:221], v235 offset:22528
	ds_read_b128 v[236:239], v235 offset:23552
	global_load_lds_dwordx4 v[168:169], off
	s_add_i32 m0, s61, 0x2000
	s_add_u32 s78, s50, 0x80000
	v_lshl_add_u64 v[222:223], s[50:51], 0, v[186:187]
	s_addc_u32 s79, s51, 0
	s_add_i32 s61, s63, s73
	global_load_lds_dwordx4 v[222:223], off
	v_lshl_add_u64 v[2:3], s[78:79], 0, v[182:183]
	s_mov_b32 m0, s61
	v_lshl_add_u64 v[244:245], s[76:77], 0, v[180:181]
	global_load_lds_dwordx4 v[2:3], off
	v_lshl_add_u64 v[2:3], s[78:79], 0, v[186:187]
	s_add_i32 m0, s61, 0x2000
	v_lshl_add_u64 v[246:247], s[76:77], 0, v[184:185]
	global_load_lds_dwordx4 v[2:3], off
	s_mov_b32 m0, s82
	s_nop 0
	global_load_lds_dwordx4 v[244:245], off
	s_mov_b32 m0, s83
	s_nop 0
	global_load_lds_dwordx4 v[246:247], off
	s_waitcnt vmcnt(8) lgkmcnt(0)
	s_setprio 1
	s_barrier
; #define PG8_STAGE(bufoff, gbase, voff) do { _Pragma("unroll") for (int _i = 0; _i < 2; ++_i) \
;         __builtin_amdgcn_global_load_lds((const unsigned*)((const char*)(gbase) + (voff)[_i]), (PG8_LAS unsigned*)(lds + (bufoff) + ldsw + _i * 8192), 16, 0, 0); } while (0)
; #define PG8_LDA(dst, b, h) do { _Pragma("unroll") for (int m = 0; m < 4; ++m) _Pragma("unroll") for (int k = 0; k < 2; ++k) dst[m][k] = *(const PG8_LAS bf16x8*)(lds + PG8_SA(b, h) + aoff + m * 2048 + k * 1024); } while (0)
; #define PG8_LDB(dst, b, h) do { _Pragma("unroll") for (int n = 0; n < 2; ++n) _Pragma("unroll") for (int k = 0; k < 2; ++k) dst[n][k] = *(const PG8_LAS bf16x8*)(lds + PG8_SB(b, h) + boff + n * 2048 + k * 1024); } while (0)
; #define PG8_MMA(ai, bj, At, Bt) do { __builtin_amdgcn_s_setprio(1); _Pragma("unroll") for (int m = 0; m < 4; ++m) _Pragma("unroll") for (int n = 0; n < 2; ++n) _Pragma("unroll") for (int k = 0; k < 2; ++k) \
;         acc[ai][bj][m][n] = __builtin_amdgcn_mfma_f32_16x16x32_bf16(Bt[n][k], At[m][k], acc[ai][bj][m][n], 0, 0, 0); __builtin_amdgcn_s_setprio(0); } while (0)
; #define PG8_WAIT_V(n) asm volatile("s_waitcnt vmcnt(" #n ")" ::: "memory")
; #define PG8_WAIT_L(n) asm volatile("s_waitcnt lgkmcnt(" #n ")" ::: "memory")
; #define PG8_BAR __builtin_amdgcn_s_barrier()
; #define PG8_SCHED __builtin_amdgcn_sched_barrier(0)
; template <class Epi, class Sched, bool ALIGN_EPI = false, bool SP2 = false>
; __device__ __forceinline__ void gemm_phase(PG8_LAS unsigned char* lds, const Gemm g, const Sched& S, const Epi& E) {
;     ...
;             PG8_WAIT_V(8); PG8_WAIT_L(0); PG8_BAR; PG8_MMA(1, 0, At, B0); PG8_MMA(1, 1, At, B1); PG8_BAR; PG8_SCHED;
;             PG8_LDB(B0, 1, 0); PG8_LDB(B1, 1, 1); PG8_SCHED; PG8_LDA(At, 1, 0); PG8_STAGE(PG8_SA(0, 1), a2 + hstep, voffA);
;             PG8_WAIT_V(8); PG8_WAIT_L(0); PG8_BAR; PG8_MMA(0, 0, At, B0); PG8_MMA(0, 1, At, B1); PG8_BAR; PG8_SCHED;
	v_mfma_f32_16x16x32_bf16 v[64:67], v[124:127], v[164:167], v[64:67]
	v_mfma_f32_16x16x32_bf16 v[60:63], v[132:135], v[164:167], v[60:63]
	v_mfma_f32_16x16x32_bf16 v[48:51], v[124:127], v[202:205], v[48:51]
	v_mfma_f32_16x16x32_bf16 v[44:47], v[132:135], v[202:205], v[44:47]
	v_mfma_f32_16x16x32_bf16 v[32:35], v[124:127], v[210:213], v[32:35]
	v_mfma_f32_16x16x32_bf16 v[28:31], v[132:135], v[210:213], v[28:31]
	v_mfma_f32_16x16x32_bf16 v[16:19], v[124:127], v[218:221], v[16:19]
	v_mfma_f32_16x16x32_bf16 v[12:15], v[132:135], v[218:221], v[12:15]
	v_mfma_f32_16x16x32_bf16 v[64:67], v[128:131], v[198:201], v[64:67]
	v_mfma_f32_16x16x32_bf16 v[60:63], v[140:143], v[198:201], v[60:63]
	v_mfma_f32_16x16x32_bf16 v[48:51], v[128:131], v[206:209], v[48:51]
	v_mfma_f32_16x16x32_bf16 v[44:47], v[140:143], v[206:209], v[44:47]
	v_mfma_f32_16x16x32_bf16 v[32:35], v[128:131], v[214:217], v[32:35]
	v_mfma_f32_16x16x32_bf16 v[28:31], v[140:143], v[214:217], v[28:31]
	v_mfma_f32_16x16x32_bf16 v[16:19], v[128:131], v[236:239], v[16:19]
	v_mfma_f32_16x16x32_bf16 v[12:15], v[140:143], v[236:239], v[12:15]
	s_setprio 0
	s_setprio 1
	v_mfma_f32_16x16x32_bf16 v[56:59], v[148:151], v[164:167], v[56:59]
	v_mfma_f32_16x16x32_bf16 v[52:55], v[156:159], v[164:167], v[52:55]
	v_mfma_f32_16x16x32_bf16 v[40:43], v[148:151], v[202:205], v[40:43]
	v_mfma_f32_16x16x32_bf16 v[36:39], v[156:159], v[202:205], v[36:39]
	v_mfma_f32_16x16x32_bf16 v[24:27], v[148:151], v[210:213], v[24:27]
	v_mfma_f32_16x16x32_bf16 v[20:23], v[156:159], v[210:213], v[20:23]
	v_mfma_f32_16x16x32_bf16 v[8:11], v[148:151], v[218:221], v[8:11]
	v_mfma_f32_16x16x32_bf16 v[2:5], v[156:159], v[218:221], v[4:7]
	v_mfma_f32_16x16x32_bf16 v[56:59], v[152:155], v[198:201], v[56:59]
	v_mfma_f32_16x16x32_bf16 v[52:55], v[160:163], v[198:201], v[52:55]
	v_mfma_f32_16x16x32_bf16 v[40:43], v[152:155], v[206:209], v[40:43]
	v_mfma_f32_16x16x32_bf16 v[36:39], v[160:163], v[206:209], v[36:39]
	v_mfma_f32_16x16x32_bf16 v[24:27], v[152:155], v[214:217], v[24:27]
	v_mfma_f32_16x16x32_bf16 v[20:23], v[160:163], v[214:217], v[20:23]
	v_mfma_f32_16x16x32_bf16 v[8:11], v[152:155], v[236:239], v[8:11]
	v_mfma_f32_16x16x32_bf16 v[2:5], v[160:163], v[236:239], v[2:5]
	s_setprio 0
	s_barrier
	s_add_i32 s61, 0, 0x18000
	v_add_u32_e32 v0, s61, v234
	s_add_i32 s63, 0, 0x1c000
	ds_read_b128 v[124:127], v0
	ds_read_b128 v[128:131], v0 offset:1024
	ds_read_b128 v[132:135], v0 offset:2048
	ds_read_b128 v[140:143], v0 offset:3072
	v_add_u32_e32 v0, s63, v234
	ds_read_b128 v[148:151], v0
	ds_read_b128 v[152:155], v0 offset:1024
	ds_read_b128 v[156:159], v0 offset:2048
	ds_read_b128 v[160:163], v0 offset:3072
	s_add_u32 s76, s76, 0x80000
	s_addc_u32 s77, s77, 0
	s_mov_b32 m0, s84
	v_lshl_add_u64 v[6:7], s[76:77], 0, v[180:181]
	ds_read_b128 v[164:167], v235 offset:32768
	ds_read_b128 v[198:201], v235 offset:33792
	ds_read_b128 v[202:205], v235 offset:34816
	ds_read_b128 v[206:209], v235 offset:35840
	ds_read_b128 v[210:213], v235 offset:36864
	ds_read_b128 v[214:217], v235 offset:37888
	ds_read_b128 v[218:221], v235 offset:38912
	ds_read_b128 v[236:239], v235 offset:39936
	global_load_lds_dwordx4 v[6:7], off
	s_mov_b32 m0, s85
	v_lshl_add_u64 v[6:7], s[76:77], 0, v[184:185]
	global_load_lds_dwordx4 v[6:7], off
	s_waitcnt vmcnt(8) lgkmcnt(0)
	s_setprio 1
	s_barrier
	v_mfma_f32_16x16x32_bf16 v[144:147], v[124:127], v[164:167], v[144:147]
	v_mfma_f32_16x16x32_bf16 v[136:139], v[132:135], v[164:167], v[136:139]
	v_mfma_f32_16x16x32_bf16 v[112:115], v[124:127], v[202:205], v[112:115]
	v_mfma_f32_16x16x32_bf16 v[108:111], v[132:135], v[202:205], v[108:111]
	v_mfma_f32_16x16x32_bf16 v[96:99], v[124:127], v[210:213], v[96:99]
	v_mfma_f32_16x16x32_bf16 v[92:95], v[132:135], v[210:213], v[92:95]
	v_mfma_f32_16x16x32_bf16 v[80:83], v[124:127], v[218:221], v[80:83]
	v_mfma_f32_16x16x32_bf16 v[76:79], v[132:135], v[218:221], v[76:79]
	v_mfma_f32_16x16x32_bf16 v[144:147], v[128:131], v[198:201], v[144:147]
	v_mfma_f32_16x16x32_bf16 v[136:139], v[140:143], v[198:201], v[136:139]
	v_mfma_f32_16x16x32_bf16 v[112:115], v[128:131], v[206:209], v[112:115]
	v_mfma_f32_16x16x32_bf16 v[108:111], v[140:143], v[206:209], v[108:111]
	v_mfma_f32_16x16x32_bf16 v[96:99], v[128:131], v[214:217], v[96:99]
	v_mfma_f32_16x16x32_bf16 v[92:95], v[140:143], v[214:217], v[92:95]
	v_mfma_f32_16x16x32_bf16 v[80:83], v[128:131], v[236:239], v[80:83]
	v_mfma_f32_16x16x32_bf16 v[76:79], v[140:143], v[236:239], v[76:79]
	s_setprio 0
	s_setprio 1
	v_mfma_f32_16x16x32_bf16 v[120:123], v[148:151], v[164:167], v[120:123]
	v_mfma_f32_16x16x32_bf16 v[116:119], v[156:159], v[164:167], v[116:119]
	v_mfma_f32_16x16x32_bf16 v[104:107], v[148:151], v[202:205], v[104:107]
	v_mfma_f32_16x16x32_bf16 v[100:103], v[156:159], v[202:205], v[100:103]
	v_mfma_f32_16x16x32_bf16 v[88:91], v[148:151], v[210:213], v[88:91]
	v_mfma_f32_16x16x32_bf16 v[84:87], v[156:159], v[210:213], v[84:87]
	v_mfma_f32_16x16x32_bf16 v[72:75], v[148:151], v[218:221], v[72:75]
	v_mfma_f32_16x16x32_bf16 v[68:71], v[156:159], v[218:221], v[68:71]
	v_mfma_f32_16x16x32_bf16 v[120:123], v[152:155], v[198:201], v[120:123]
	v_mfma_f32_16x16x32_bf16 v[116:119], v[160:163], v[198:201], v[116:119]
	v_mfma_f32_16x16x32_bf16 v[104:107], v[152:155], v[206:209], v[104:107]
	v_mfma_f32_16x16x32_bf16 v[100:103], v[160:163], v[206:209], v[100:103]
	v_mfma_f32_16x16x32_bf16 v[88:91], v[152:155], v[214:217], v[88:91]
	v_mfma_f32_16x16x32_bf16 v[84:87], v[160:163], v[214:217], v[84:87]
	v_mfma_f32_16x16x32_bf16 v[72:75], v[152:155], v[236:239], v[72:75]
	v_mfma_f32_16x16x32_bf16 v[68:71], v[160:163], v[236:239], v[68:71]
	s_setprio 0
	s_barrier
; #define PG8_STAGE(bufoff, gbase, voff) do { _Pragma("unroll") for (int _i = 0; _i < 2; ++_i) \
;         __builtin_amdgcn_global_load_lds((const unsigned*)((const char*)(gbase) + (voff)[_i]), (PG8_LAS unsigned*)(lds + (bufoff) + ldsw + _i * 8192), 16, 0, 0); } while (0)
; #define PG8_LDA(dst, b, h) do { _Pragma("unroll") for (int m = 0; m < 4; ++m) _Pragma("unroll") for (int k = 0; k < 2; ++k) dst[m][k] = *(const PG8_LAS bf16x8*)(lds + PG8_SA(b, h) + aoff + m * 2048 + k * 1024); } while (0)
; #define PG8_MMA(ai, bj, At, Bt) do { __builtin_amdgcn_s_setprio(1); _Pragma("unroll") for (int m = 0; m < 4; ++m) _Pragma("unroll") for (int n = 0; n < 2; ++n) _Pragma("unroll") for (int k = 0; k < 2; ++k) \
;         acc[ai][bj][m][n] = __builtin_amdgcn_mfma_f32_16x16x32_bf16(Bt[n][k], At[m][k], acc[ai][bj][m][n], 0, 0, 0); __builtin_amdgcn_s_setprio(0); } while (0)
; #define PG8_WAIT_V(n) asm volatile("s_waitcnt vmcnt(" #n ")" ::: "memory")
; #define PG8_WAIT_L(n) asm volatile("s_waitcnt lgkmcnt(" #n ")" ::: "memory")
; #define PG8_BAR __builtin_amdgcn_s_barrier()
; #define PG8_SCHED __builtin_amdgcn_sched_barrier(0)
; template <class Epi, class Sched, bool ALIGN_EPI = false, bool SP2 = false>
; __device__ __forceinline__ void gemm_phase(PG8_LAS unsigned char* lds, const Gemm g, const Sched& S, const Epi& E) {
;     ...
;             PG8_LDA(At, 1, 1); PG8_STAGE(PG8_SB(1, 0), b3, voffB); PG8_STAGE(PG8_SB(1, 1), b3 + hstep, voffB); PG8_STAGE(PG8_SA(1, 0), a3, voffA);
;             PG8_WAIT_V(8); PG8_WAIT_L(0); PG8_BAR; PG8_MMA(1, 0, At, B0); PG8_MMA(1, 1, At, B1); PG8_BAR; PG8_SCHED;
;     ...
;         }
;         if constexpr (ALIGN_EPI) { if (wr == 0) PG8_BAR; }
	s_add_i32 s61, s61, s73
	v_lshl_add_u64 v[6:7], v[168:169], 0, s[12:13]
	s_mov_b32 m0, s61
	ds_read_b128 v[164:167], v235 offset:49152
	ds_read_b128 v[198:201], v235 offset:50176
	ds_read_b128 v[202:205], v235 offset:51200
	ds_read_b128 v[206:209], v235 offset:52224
	ds_read_b128 v[210:213], v235 offset:53248
	ds_read_b128 v[214:217], v235 offset:54272
	ds_read_b128 v[218:221], v235 offset:55296
	ds_read_b128 v[236:239], v235 offset:56320
	global_load_lds_dwordx4 v[6:7], off
	s_add_i32 m0, s61, 0x2000
	s_add_u32 s50, s50, 0x80080
	v_lshl_add_u64 v[6:7], v[222:223], 0, s[12:13]
	s_addc_u32 s51, s51, 0
	s_add_i32 s61, s63, s73
	global_load_lds_dwordx4 v[6:7], off
	s_mov_b32 m0, s61
	v_lshl_add_u64 v[6:7], s[50:51], 0, v[182:183]
	global_load_lds_dwordx4 v[6:7], off
	s_add_i32 m0, s61, 0x2000
	v_lshl_add_u64 v[6:7], s[50:51], 0, v[186:187]
	global_load_lds_dwordx4 v[6:7], off
	s_mov_b32 m0, s87
	v_lshl_add_u64 v[6:7], v[244:245], 0, s[12:13]
	global_load_lds_dwordx4 v[6:7], off
	s_mov_b32 m0, s88
	v_lshl_add_u64 v[6:7], v[246:247], 0, s[12:13]
	global_load_lds_dwordx4 v[6:7], off
	s_waitcnt vmcnt(8) lgkmcnt(0)
	s_setprio 1
	s_barrier
	v_mfma_f32_16x16x32_bf16 v[64:67], v[124:127], v[164:167], v[64:67]
	v_mfma_f32_16x16x32_bf16 v[60:63], v[132:135], v[164:167], v[60:63]
	v_mfma_f32_16x16x32_bf16 v[48:51], v[124:127], v[202:205], v[48:51]
	v_mfma_f32_16x16x32_bf16 v[44:47], v[132:135], v[202:205], v[44:47]
	v_mfma_f32_16x16x32_bf16 v[32:35], v[124:127], v[210:213], v[32:35]
	v_mfma_f32_16x16x32_bf16 v[28:31], v[132:135], v[210:213], v[28:31]
	v_mfma_f32_16x16x32_bf16 v[16:19], v[124:127], v[218:221], v[16:19]
	v_mfma_f32_16x16x32_bf16 v[12:15], v[132:135], v[218:221], v[12:15]
	v_mfma_f32_16x16x32_bf16 v[64:67], v[128:131], v[198:201], v[64:67]
	v_mfma_f32_16x16x32_bf16 v[60:63], v[140:143], v[198:201], v[60:63]
	v_mfma_f32_16x16x32_bf16 v[48:51], v[128:131], v[206:209], v[48:51]
	v_mfma_f32_16x16x32_bf16 v[44:47], v[140:143], v[206:209], v[44:47]
	v_mfma_f32_16x16x32_bf16 v[32:35], v[128:131], v[214:217], v[32:35]
	v_mfma_f32_16x16x32_bf16 v[28:31], v[140:143], v[214:217], v[28:31]
	v_mfma_f32_16x16x32_bf16 v[16:19], v[128:131], v[236:239], v[16:19]
	v_mfma_f32_16x16x32_bf16 v[12:15], v[140:143], v[236:239], v[12:15]
	s_setprio 0
	s_setprio 1
	v_mfma_f32_16x16x32_bf16 v[56:59], v[148:151], v[164:167], v[56:59]
	v_mfma_f32_16x16x32_bf16 v[52:55], v[156:159], v[164:167], v[52:55]
	v_mfma_f32_16x16x32_bf16 v[40:43], v[148:151], v[202:205], v[40:43]
	v_mfma_f32_16x16x32_bf16 v[36:39], v[156:159], v[202:205], v[36:39]
	v_mfma_f32_16x16x32_bf16 v[24:27], v[148:151], v[210:213], v[24:27]
	v_mfma_f32_16x16x32_bf16 v[20:23], v[156:159], v[210:213], v[20:23]
	v_mfma_f32_16x16x32_bf16 v[6:9], v[148:151], v[218:221], v[8:11]
	v_mfma_f32_16x16x32_bf16 v[2:5], v[156:159], v[218:221], v[2:5]
	v_mfma_f32_16x16x32_bf16 v[56:59], v[152:155], v[198:201], v[56:59]
	v_mfma_f32_16x16x32_bf16 v[52:55], v[160:163], v[198:201], v[52:55]
	v_mfma_f32_16x16x32_bf16 v[40:43], v[152:155], v[206:209], v[40:43]
	v_mfma_f32_16x16x32_bf16 v[36:39], v[160:163], v[206:209], v[36:39]
	v_mfma_f32_16x16x32_bf16 v[24:27], v[152:155], v[214:217], v[24:27]
	v_mfma_f32_16x16x32_bf16 v[20:23], v[160:163], v[214:217], v[20:23]
	v_mfma_f32_16x16x32_bf16 v[8:11], v[152:155], v[236:239], v[6:9]
	v_mfma_f32_16x16x32_bf16 v[4:7], v[160:163], v[236:239], v[2:5]
	s_setprio 0
	s_barrier
	s_add_i32 s58, s58, 2
	s_add_u32 s48, s48, 0x100
	s_addc_u32 s49, s49, 0
	s_add_u32 s39, s39, 0x100
	s_addc_u32 s47, s47, 0
	s_cmp_gt_u32 s58, 29
	s_cbranch_scc0 .LBB0_117
	s_and_b64 vcc, exec, s[30:31]
	s_cbranch_vccz .LBB0_120
	s_barrier

; #define PG8_STAGE(bufoff, gbase, voff) do { _Pragma("unroll") for (int _i = 0; _i < 2; ++_i) \
;         __builtin_amdgcn_global_load_lds((const unsigned*)((const char*)(gbase) + (voff)[_i]), (PG8_LAS unsigned*)(lds + (bufoff) + ldsw + _i * 8192), 16, 0, 0); } while (0)
; #define PG8_LDA(dst, b, h) do { _Pragma("unroll") for (int m = 0; m < 4; ++m) _Pragma("unroll") for (int k = 0; k < 2; ++k) dst[m][k] = *(const PG8_LAS bf16x8*)(lds + PG8_SA(b, h) + aoff + m * 2048 + k * 1024); } while (0)
; #define PG8_LDB(dst, b, h) do { _Pragma("unroll") for (int n = 0; n < 2; ++n) _Pragma("unroll") for (int k = 0; k < 2; ++k) dst[n][k] = *(const PG8_LAS bf16x8*)(lds + PG8_SB(b, h) + boff + n * 2048 + k * 1024); } while (0)
; #define PG8_MMA(ai, bj, At, Bt) do { __builtin_amdgcn_s_setprio(1); _Pragma("unroll") for (int m = 0; m < 4; ++m) _Pragma("unroll") for (int n = 0; n < 2; ++n) _Pragma("unroll") for (int k = 0; k < 2; ++k) \
;         acc[ai][bj][m][n] = __builtin_amdgcn_mfma_f32_16x16x32_bf16(Bt[n][k], At[m][k], acc[ai][bj][m][n], 0, 0, 0); __builtin_amdgcn_s_setprio(0); } while (0)
; #define PG8_WAIT_V(n) asm volatile("s_waitcnt vmcnt(" #n ")" ::: "memory")
; #define PG8_WAIT_L(n) asm volatile("s_waitcnt lgkmcnt(" #n ")" ::: "memory")
; #define PG8_BAR __builtin_amdgcn_s_barrier()
; #define PG8_SCHED __builtin_amdgcn_sched_barrier(0)
; template <class Epi, class Sched, bool ALIGN_EPI = false, bool SP2 = false>
; __device__ __forceinline__ void gemm_phase(PG8_LAS unsigned char* lds, const Gemm g, const Sched& S, const Epi& E) {
;     ...
;         for (int t = 0; t < nt; t += 2) {
;             const bool last = (t == nt - 2);
;             const char* a1 = cA + (size_t)(t + 1) * kstep;
;             const char* a2 = last ? nA : cA + (size_t)(t + 2) * kstep; const char* b2 = last ? nB : cB + (size_t)(t + 2) * kstep;
;             const char* a3 = a2 + kstep; const char* b3 = b2 + kstep;
;             if (last && has_next) S.a_ready(nxt);
;             if constexpr (SP2) {
;             PG8_LDB(B0, 0, 0); PG8_LDB(B1, 0, 1); PG8_SCHED; PG8_LDA(At, 0, 0); PG8_STAGE(PG8_SA(1, 1), a1 + hstep, voffA);
;             PG8_WAIT_V(8); PG8_WAIT_L(0); PG8_BAR; PG8_MMA(0, 0, At, B0); PG8_MMA(0, 1, At, B1); PG8_BAR; PG8_SCHED;
;             PG8_LDA(At, 0, 1); PG8_STAGE(PG8_SB(0, 0), b2, voffB); PG8_STAGE(PG8_SB(0, 1), b2 + hstep, voffB); PG8_STAGE(PG8_SA(0, 0), a2, voffA);
.LBB0_1427:
	s_add_i32 s96, s74, 2
	s_add_u32 s97, s44, 0x80
	s_addc_u32 s75, s45, 0
	s_add_i32 s27, 0, 0x10000
	s_cmp_eq_u32 s91, s74
	s_cselect_b32 s75, s24, s75
	s_cselect_b32 s74, s25, s97
	s_cselect_b32 vcc_hi, s53, s95
	s_cselect_b32 vcc_lo, s61, s94
	s_add_i32 s97, 0, 0x14000
	v_add_u32_e32 v142, s27, v185
	v_add_u32_e32 v168, s97, v185
	ds_read_b128 v[130:133], v142
	ds_read_b128 v[134:137], v142 offset:1024
	ds_read_b128 v[138:141], v142 offset:2048
	ds_read_b128 v[142:145], v142 offset:3072
	ds_read_b128 v[146:149], v168
	ds_read_b128 v[150:153], v168 offset:1024
	ds_read_b128 v[164:167], v168 offset:2048
	ds_read_b128 v[180:183], v168 offset:3072
	v_lshl_add_u64 v[168:169], s[44:45], 0, v[160:161]
	s_add_i32 m0, s83, 0xc000
	ds_read_b128 v[190:193], v187
	ds_read_b128 v[194:197], v187 offset:1024
	ds_read_b128 v[198:201], v187 offset:2048
	ds_read_b128 v[202:205], v187 offset:3072
	ds_read_b128 v[206:209], v187 offset:4096
	ds_read_b128 v[210:213], v187 offset:5120
	ds_read_b128 v[214:217], v187 offset:6144
	ds_read_b128 v[218:221], v187 offset:7168
	global_load_lds_dwordx4 v[168:169], off
	s_add_i32 m0, s83, 0xe000
	v_lshl_add_u64 v[168:169], s[44:45], 0, v[162:163]
	global_load_lds_dwordx4 v[168:169], off
	s_waitcnt vmcnt(8) lgkmcnt(0)
	s_setprio 1
	s_barrier
	v_mfma_f32_16x16x32_bf16 v[126:129], v[130:133], v[190:193], v[126:129]
	v_mfma_f32_16x16x32_bf16 v[122:125], v[138:141], v[190:193], v[122:125]
	v_mfma_f32_16x16x32_bf16 v[110:113], v[130:133], v[198:201], v[110:113]
	v_mfma_f32_16x16x32_bf16 v[106:109], v[138:141], v[198:201], v[106:109]
	v_mfma_f32_16x16x32_bf16 v[94:97], v[130:133], v[206:209], v[94:97]
	v_mfma_f32_16x16x32_bf16 v[90:93], v[138:141], v[206:209], v[90:93]
	v_mfma_f32_16x16x32_bf16 v[78:81], v[130:133], v[214:217], v[78:81]
	v_mfma_f32_16x16x32_bf16 v[74:77], v[138:141], v[214:217], v[74:77]
	v_mfma_f32_16x16x32_bf16 v[126:129], v[134:137], v[194:197], v[126:129]
	v_mfma_f32_16x16x32_bf16 v[122:125], v[142:145], v[194:197], v[122:125]
	v_mfma_f32_16x16x32_bf16 v[110:113], v[134:137], v[202:205], v[110:113]
	v_mfma_f32_16x16x32_bf16 v[106:109], v[142:145], v[202:205], v[106:109]
	v_mfma_f32_16x16x32_bf16 v[94:97], v[134:137], v[210:213], v[94:97]
	v_mfma_f32_16x16x32_bf16 v[90:93], v[142:145], v[210:213], v[90:93]
	v_mfma_f32_16x16x32_bf16 v[78:81], v[134:137], v[218:221], v[78:81]
	v_mfma_f32_16x16x32_bf16 v[74:77], v[142:145], v[218:221], v[74:77]
	s_setprio 0
	s_setprio 1
	v_mfma_f32_16x16x32_bf16 v[118:121], v[146:149], v[190:193], v[118:121]
	v_mfma_f32_16x16x32_bf16 v[114:117], v[164:167], v[190:193], v[114:117]
	v_mfma_f32_16x16x32_bf16 v[102:105], v[146:149], v[198:201], v[102:105]
	v_mfma_f32_16x16x32_bf16 v[98:101], v[164:167], v[198:201], v[98:101]
	v_mfma_f32_16x16x32_bf16 v[86:89], v[146:149], v[206:209], v[86:89]
	v_mfma_f32_16x16x32_bf16 v[82:85], v[164:167], v[206:209], v[82:85]
	v_mfma_f32_16x16x32_bf16 v[70:73], v[146:149], v[214:217], v[70:73]
	v_mfma_f32_16x16x32_bf16 v[66:69], v[164:167], v[214:217], v[66:69]
	v_mfma_f32_16x16x32_bf16 v[118:121], v[150:153], v[194:197], v[118:121]
	v_mfma_f32_16x16x32_bf16 v[114:117], v[180:183], v[194:197], v[114:117]
	v_mfma_f32_16x16x32_bf16 v[102:105], v[150:153], v[202:205], v[102:105]
	v_mfma_f32_16x16x32_bf16 v[98:101], v[180:183], v[202:205], v[98:101]
	v_mfma_f32_16x16x32_bf16 v[86:89], v[150:153], v[210:213], v[86:89]
	v_mfma_f32_16x16x32_bf16 v[82:85], v[180:183], v[210:213], v[82:85]
	v_mfma_f32_16x16x32_bf16 v[70:73], v[150:153], v[218:221], v[70:73]
	v_mfma_f32_16x16x32_bf16 v[66:69], v[180:183], v[218:221], v[66:69]
	s_setprio 0
	s_barrier
	s_add_i32 s27, s27, s82
	v_lshl_add_u64 v[168:169], vcc, 0, v[0:1]
	s_mov_b32 m0, s27
	ds_read_b128 v[190:193], v187 offset:16384
	ds_read_b128 v[194:197], v187 offset:17408
	ds_read_b128 v[198:201], v187 offset:18432
	ds_read_b128 v[202:205], v187 offset:19456
	ds_read_b128 v[206:209], v187 offset:20480
	ds_read_b128 v[210:213], v187 offset:21504
	ds_read_b128 v[214:217], v187 offset:22528
	ds_read_b128 v[218:221], v187 offset:23552
	global_load_lds_dwordx4 v[168:169], off
	s_add_i32 m0, s27, 0x2000
	v_lshl_add_u64 v[222:223], vcc, 0, v[154:155]
	s_add_u32 vcc_lo, vcc_lo, s70
	s_addc_u32 vcc_hi, vcc_hi, 0
	s_add_i32 s27, s97, s82
	global_load_lds_dwordx4 v[222:223], off
	v_lshl_add_u64 v[232:233], vcc, 0, v[0:1]
	s_mov_b32 m0, s27
	v_lshl_add_u64 v[234:235], vcc, 0, v[154:155]
	global_load_lds_dwordx4 v[232:233], off
	s_add_i32 m0, s27, 0x2000
	v_lshl_add_u64 v[236:237], s[74:75], 0, v[158:159]
	global_load_lds_dwordx4 v[234:235], off
	s_mov_b32 m0, s83
	v_lshl_add_u64 v[238:239], s[74:75], 0, v[156:157]
	global_load_lds_dwordx4 v[236:237], off
	s_mov_b32 m0, s84
	s_nop 0
	global_load_lds_dwordx4 v[238:239], off
	s_waitcnt vmcnt(8) lgkmcnt(0)
	s_setprio 1
	s_barrier
; #define PG8_STAGE(bufoff, gbase, voff) do { _Pragma("unroll") for (int _i = 0; _i < 2; ++_i) \
;         __builtin_amdgcn_global_load_lds((const unsigned*)((const char*)(gbase) + (voff)[_i]), (PG8_LAS unsigned*)(lds + (bufoff) + ldsw + _i * 8192), 16, 0, 0); } while (0)
; #define PG8_LDA(dst, b, h) do { _Pragma("unroll") for (int m = 0; m < 4; ++m) _Pragma("unroll") for (int k = 0; k < 2; ++k) dst[m][k] = *(const PG8_LAS bf16x8*)(lds + PG8_SA(b, h) + aoff + m * 2048 + k * 1024); } while (0)
; #define PG8_LDB(dst, b, h) do { _Pragma("unroll") for (int n = 0; n < 2; ++n) _Pragma("unroll") for (int k = 0; k < 2; ++k) dst[n][k] = *(const PG8_LAS bf16x8*)(lds + PG8_SB(b, h) + boff + n * 2048 + k * 1024); } while (0)
; #define PG8_MMA(ai, bj, At, Bt) do { __builtin_amdgcn_s_setprio(1); _Pragma("unroll") for (int m = 0; m < 4; ++m) _Pragma("unroll") for (int n = 0; n < 2; ++n) _Pragma("unroll") for (int k = 0; k < 2; ++k) \
;         acc[ai][bj][m][n] = __builtin_amdgcn_mfma_f32_16x16x32_bf16(Bt[n][k], At[m][k], acc[ai][bj][m][n], 0, 0, 0); __builtin_amdgcn_s_setprio(0); } while (0)
; #define PG8_WAIT_V(n) asm volatile("s_waitcnt vmcnt(" #n ")" ::: "memory")
; #define PG8_WAIT_L(n) asm volatile("s_waitcnt lgkmcnt(" #n ")" ::: "memory")
; #define PG8_BAR __builtin_amdgcn_s_barrier()
; #define PG8_SCHED __builtin_amdgcn_sched_barrier(0)
; template <class Epi, class Sched, bool ALIGN_EPI = false, bool SP2 = false>
; __device__ __forceinline__ void gemm_phase(PG8_LAS unsigned char* lds, const Gemm g, const Sched& S, const Epi& E) {
;     ...
;             PG8_WAIT_V(8); PG8_WAIT_L(0); PG8_BAR; PG8_MMA(1, 0, At, B0); PG8_MMA(1, 1, At, B1); PG8_BAR; PG8_SCHED;
;             PG8_LDB(B0, 1, 0); PG8_LDB(B1, 1, 1); PG8_SCHED; PG8_LDA(At, 1, 0); PG8_STAGE(PG8_SA(0, 1), a2 + hstep, voffA);
;             PG8_WAIT_V(8); PG8_WAIT_L(0); PG8_BAR; PG8_MMA(0, 0, At, B0); PG8_MMA(0, 1, At, B1); PG8_BAR; PG8_SCHED;
	v_mfma_f32_16x16x32_bf16 v[62:65], v[130:133], v[190:193], v[62:65]
	v_mfma_f32_16x16x32_bf16 v[58:61], v[138:141], v[190:193], v[58:61]
	v_mfma_f32_16x16x32_bf16 v[46:49], v[130:133], v[198:201], v[46:49]
	v_mfma_f32_16x16x32_bf16 v[42:45], v[138:141], v[198:201], v[42:45]
	v_mfma_f32_16x16x32_bf16 v[30:33], v[130:133], v[206:209], v[30:33]
	v_mfma_f32_16x16x32_bf16 v[26:29], v[138:141], v[206:209], v[26:29]
	v_mfma_f32_16x16x32_bf16 v[14:17], v[130:133], v[214:217], v[14:17]
	v_mfma_f32_16x16x32_bf16 v[10:13], v[138:141], v[214:217], v[10:13]
	v_mfma_f32_16x16x32_bf16 v[62:65], v[134:137], v[194:197], v[62:65]
	v_mfma_f32_16x16x32_bf16 v[58:61], v[142:145], v[194:197], v[58:61]
	v_mfma_f32_16x16x32_bf16 v[46:49], v[134:137], v[202:205], v[46:49]
	v_mfma_f32_16x16x32_bf16 v[42:45], v[142:145], v[202:205], v[42:45]
	v_mfma_f32_16x16x32_bf16 v[30:33], v[134:137], v[210:213], v[30:33]
	v_mfma_f32_16x16x32_bf16 v[26:29], v[142:145], v[210:213], v[26:29]
	v_mfma_f32_16x16x32_bf16 v[14:17], v[134:137], v[218:221], v[14:17]
	v_mfma_f32_16x16x32_bf16 v[10:13], v[142:145], v[218:221], v[10:13]
	s_setprio 0
	s_setprio 1
	v_mfma_f32_16x16x32_bf16 v[54:57], v[146:149], v[190:193], v[54:57]
	v_mfma_f32_16x16x32_bf16 v[50:53], v[164:167], v[190:193], v[50:53]
	v_mfma_f32_16x16x32_bf16 v[38:41], v[146:149], v[198:201], v[38:41]
	v_mfma_f32_16x16x32_bf16 v[34:37], v[164:167], v[198:201], v[34:37]
	v_mfma_f32_16x16x32_bf16 v[22:25], v[146:149], v[206:209], v[22:25]
	v_mfma_f32_16x16x32_bf16 v[18:21], v[164:167], v[206:209], v[18:21]
	v_mfma_f32_16x16x32_bf16 v[6:9], v[146:149], v[214:217], v[6:9]
	v_mfma_f32_16x16x32_bf16 v[2:5], v[164:167], v[214:217], v[2:5]
	v_mfma_f32_16x16x32_bf16 v[54:57], v[150:153], v[194:197], v[54:57]
	v_mfma_f32_16x16x32_bf16 v[50:53], v[180:183], v[194:197], v[50:53]
	v_mfma_f32_16x16x32_bf16 v[38:41], v[150:153], v[202:205], v[38:41]
	v_mfma_f32_16x16x32_bf16 v[34:37], v[180:183], v[202:205], v[34:37]
	v_mfma_f32_16x16x32_bf16 v[22:25], v[150:153], v[210:213], v[22:25]
	v_mfma_f32_16x16x32_bf16 v[18:21], v[180:183], v[210:213], v[18:21]
	v_mfma_f32_16x16x32_bf16 v[6:9], v[150:153], v[218:221], v[6:9]
	v_mfma_f32_16x16x32_bf16 v[2:5], v[180:183], v[218:221], v[2:5]
	s_setprio 0
	s_barrier
	s_add_i32 s27, 0, 0x18000
	s_add_i32 s97, 0, 0x1c000
	v_add_u32_e32 v142, s27, v185
	v_add_u32_e32 v180, s97, v185
	ds_read_b128 v[130:133], v142
	ds_read_b128 v[134:137], v142 offset:1024
	ds_read_b128 v[138:141], v142 offset:2048
	ds_read_b128 v[142:145], v142 offset:3072
	ds_read_b128 v[146:149], v180
	ds_read_b128 v[150:153], v180 offset:1024
	ds_read_b128 v[164:167], v180 offset:2048
	ds_read_b128 v[180:183], v180 offset:3072
	s_add_u32 s74, s74, s70
	s_addc_u32 s75, s75, 0
	s_mov_b32 m0, s85
	v_lshl_add_u64 v[244:245], s[74:75], 0, v[158:159]
	ds_read_b128 v[190:193], v187 offset:32768
	ds_read_b128 v[194:197], v187 offset:33792
	ds_read_b128 v[198:201], v187 offset:34816
	ds_read_b128 v[202:205], v187 offset:35840
	ds_read_b128 v[206:209], v187 offset:36864
	ds_read_b128 v[210:213], v187 offset:37888
	ds_read_b128 v[214:217], v187 offset:38912
	ds_read_b128 v[218:221], v187 offset:39936
	global_load_lds_dwordx4 v[244:245], off
	s_mov_b32 m0, s86
	v_lshl_add_u64 v[244:245], s[74:75], 0, v[156:157]
	global_load_lds_dwordx4 v[244:245], off
	s_waitcnt vmcnt(8) lgkmcnt(0)
	s_setprio 1
	s_barrier
	v_mfma_f32_16x16x32_bf16 v[126:129], v[130:133], v[190:193], v[126:129]
	v_mfma_f32_16x16x32_bf16 v[122:125], v[138:141], v[190:193], v[122:125]
	v_mfma_f32_16x16x32_bf16 v[110:113], v[130:133], v[198:201], v[110:113]
	v_mfma_f32_16x16x32_bf16 v[106:109], v[138:141], v[198:201], v[106:109]
	v_mfma_f32_16x16x32_bf16 v[94:97], v[130:133], v[206:209], v[94:97]
	v_mfma_f32_16x16x32_bf16 v[90:93], v[138:141], v[206:209], v[90:93]
	v_mfma_f32_16x16x32_bf16 v[78:81], v[130:133], v[214:217], v[78:81]
	v_mfma_f32_16x16x32_bf16 v[74:77], v[138:141], v[214:217], v[74:77]
	v_mfma_f32_16x16x32_bf16 v[126:129], v[134:137], v[194:197], v[126:129]
	v_mfma_f32_16x16x32_bf16 v[122:125], v[142:145], v[194:197], v[122:125]
	v_mfma_f32_16x16x32_bf16 v[110:113], v[134:137], v[202:205], v[110:113]
	v_mfma_f32_16x16x32_bf16 v[106:109], v[142:145], v[202:205], v[106:109]
	v_mfma_f32_16x16x32_bf16 v[94:97], v[134:137], v[210:213], v[94:97]
	v_mfma_f32_16x16x32_bf16 v[90:93], v[142:145], v[210:213], v[90:93]
	v_mfma_f32_16x16x32_bf16 v[78:81], v[134:137], v[218:221], v[78:81]
	v_mfma_f32_16x16x32_bf16 v[74:77], v[142:145], v[218:221], v[74:77]
	s_setprio 0
	s_setprio 1
	v_mfma_f32_16x16x32_bf16 v[118:121], v[146:149], v[190:193], v[118:121]
	v_mfma_f32_16x16x32_bf16 v[114:117], v[164:167], v[190:193], v[114:117]
	v_mfma_f32_16x16x32_bf16 v[102:105], v[146:149], v[198:201], v[102:105]
	v_mfma_f32_16x16x32_bf16 v[98:101], v[164:167], v[198:201], v[98:101]
	v_mfma_f32_16x16x32_bf16 v[86:89], v[146:149], v[206:209], v[86:89]
	v_mfma_f32_16x16x32_bf16 v[82:85], v[164:167], v[206:209], v[82:85]
	v_mfma_f32_16x16x32_bf16 v[70:73], v[146:149], v[214:217], v[70:73]
	v_mfma_f32_16x16x32_bf16 v[66:69], v[164:167], v[214:217], v[66:69]
	v_mfma_f32_16x16x32_bf16 v[118:121], v[150:153], v[194:197], v[118:121]
	v_mfma_f32_16x16x32_bf16 v[114:117], v[180:183], v[194:197], v[114:117]
	v_mfma_f32_16x16x32_bf16 v[102:105], v[150:153], v[202:205], v[102:105]
	v_mfma_f32_16x16x32_bf16 v[98:101], v[180:183], v[202:205], v[98:101]
	v_mfma_f32_16x16x32_bf16 v[86:89], v[150:153], v[210:213], v[86:89]
	v_mfma_f32_16x16x32_bf16 v[82:85], v[180:183], v[210:213], v[82:85]
	v_mfma_f32_16x16x32_bf16 v[70:73], v[150:153], v[218:221], v[70:73]
	v_mfma_f32_16x16x32_bf16 v[66:69], v[180:183], v[218:221], v[66:69]
	s_setprio 0
	s_barrier
; #define PG8_STAGE(bufoff, gbase, voff) do { _Pragma("unroll") for (int _i = 0; _i < 2; ++_i) \
;         __builtin_amdgcn_global_load_lds((const unsigned*)((const char*)(gbase) + (voff)[_i]), (PG8_LAS unsigned*)(lds + (bufoff) + ldsw + _i * 8192), 16, 0, 0); } while (0)
; #define PG8_LDA(dst, b, h) do { _Pragma("unroll") for (int m = 0; m < 4; ++m) _Pragma("unroll") for (int k = 0; k < 2; ++k) dst[m][k] = *(const PG8_LAS bf16x8*)(lds + PG8_SA(b, h) + aoff + m * 2048 + k * 1024); } while (0)
; #define PG8_MMA(ai, bj, At, Bt) do { __builtin_amdgcn_s_setprio(1); _Pragma("unroll") for (int m = 0; m < 4; ++m) _Pragma("unroll") for (int n = 0; n < 2; ++n) _Pragma("unroll") for (int k = 0; k < 2; ++k) \
;         acc[ai][bj][m][n] = __builtin_amdgcn_mfma_f32_16x16x32_bf16(Bt[n][k], At[m][k], acc[ai][bj][m][n], 0, 0, 0); __builtin_amdgcn_s_setprio(0); } while (0)
; #define PG8_WAIT_V(n) asm volatile("s_waitcnt vmcnt(" #n ")" ::: "memory")
; #define PG8_WAIT_L(n) asm volatile("s_waitcnt lgkmcnt(" #n ")" ::: "memory")
; #define PG8_BAR __builtin_amdgcn_s_barrier()
; #define PG8_SCHED __builtin_amdgcn_sched_barrier(0)
; template <class Epi, class Sched, bool ALIGN_EPI = false, bool SP2 = false>
; __device__ __forceinline__ void gemm_phase(PG8_LAS unsigned char* lds, const Gemm g, const Sched& S, const Epi& E) {
;     ...
;             PG8_LDA(At, 1, 1); PG8_STAGE(PG8_SB(1, 0), b3, voffB); PG8_STAGE(PG8_SB(1, 1), b3 + hstep, voffB); PG8_STAGE(PG8_SA(1, 0), a3, voffA);
;             PG8_WAIT_V(8); PG8_WAIT_L(0); PG8_BAR; PG8_MMA(1, 0, At, B0); PG8_MMA(1, 1, At, B1); PG8_BAR; PG8_SCHED;
;     ...
;         }
;         if constexpr (ALIGN_EPI) { if (wr == 0) PG8_BAR; }
	s_add_i32 s27, s27, s82
	v_lshl_add_u64 v[168:169], v[168:169], 0, s[12:13]
	s_mov_b32 m0, s27
	ds_read_b128 v[190:193], v187 offset:49152
	ds_read_b128 v[194:197], v187 offset:50176
	ds_read_b128 v[198:201], v187 offset:51200
	ds_read_b128 v[202:205], v187 offset:52224
	ds_read_b128 v[206:209], v187 offset:53248
	ds_read_b128 v[210:213], v187 offset:54272
	ds_read_b128 v[214:217], v187 offset:55296
	ds_read_b128 v[218:221], v187 offset:56320
	global_load_lds_dwordx4 v[168:169], off
	v_lshl_add_u64 v[168:169], v[222:223], 0, s[12:13]
	s_add_i32 m0, s27, 0x2000
	s_add_i32 s27, s97, s82
	global_load_lds_dwordx4 v[168:169], off
	s_mov_b32 m0, s27
	v_lshl_add_u64 v[168:169], v[232:233], 0, s[12:13]
	global_load_lds_dwordx4 v[168:169], off
	s_add_i32 m0, s27, 0x2000
	v_lshl_add_u64 v[168:169], v[234:235], 0, s[12:13]
	global_load_lds_dwordx4 v[168:169], off
	s_mov_b32 m0, s89
	v_lshl_add_u64 v[168:169], v[236:237], 0, s[12:13]
	global_load_lds_dwordx4 v[168:169], off
	s_mov_b32 m0, s90
	v_lshl_add_u64 v[168:169], v[238:239], 0, s[12:13]
	global_load_lds_dwordx4 v[168:169], off
	s_waitcnt vmcnt(8) lgkmcnt(0)
	s_setprio 1
	s_barrier
	v_mfma_f32_16x16x32_bf16 v[62:65], v[130:133], v[190:193], v[62:65]
	v_mfma_f32_16x16x32_bf16 v[58:61], v[138:141], v[190:193], v[58:61]
	v_mfma_f32_16x16x32_bf16 v[46:49], v[130:133], v[198:201], v[46:49]
	v_mfma_f32_16x16x32_bf16 v[42:45], v[138:141], v[198:201], v[42:45]
	v_mfma_f32_16x16x32_bf16 v[30:33], v[130:133], v[206:209], v[30:33]
	v_mfma_f32_16x16x32_bf16 v[26:29], v[138:141], v[206:209], v[26:29]
	v_mfma_f32_16x16x32_bf16 v[14:17], v[130:133], v[214:217], v[14:17]
	v_mfma_f32_16x16x32_bf16 v[10:13], v[138:141], v[214:217], v[10:13]
	v_mfma_f32_16x16x32_bf16 v[62:65], v[134:137], v[194:197], v[62:65]
	v_mfma_f32_16x16x32_bf16 v[58:61], v[142:145], v[194:197], v[58:61]
	v_mfma_f32_16x16x32_bf16 v[46:49], v[134:137], v[202:205], v[46:49]
	v_mfma_f32_16x16x32_bf16 v[42:45], v[142:145], v[202:205], v[42:45]
	v_mfma_f32_16x16x32_bf16 v[30:33], v[134:137], v[210:213], v[30:33]
	v_mfma_f32_16x16x32_bf16 v[26:29], v[142:145], v[210:213], v[26:29]
	v_mfma_f32_16x16x32_bf16 v[14:17], v[134:137], v[218:221], v[14:17]
	v_mfma_f32_16x16x32_bf16 v[10:13], v[142:145], v[218:221], v[10:13]
	s_setprio 0
	s_setprio 1
	v_mfma_f32_16x16x32_bf16 v[54:57], v[146:149], v[190:193], v[54:57]
	v_mfma_f32_16x16x32_bf16 v[50:53], v[164:167], v[190:193], v[50:53]
	v_mfma_f32_16x16x32_bf16 v[38:41], v[146:149], v[198:201], v[38:41]
	v_mfma_f32_16x16x32_bf16 v[34:37], v[164:167], v[198:201], v[34:37]
	v_mfma_f32_16x16x32_bf16 v[22:25], v[146:149], v[206:209], v[22:25]
	v_mfma_f32_16x16x32_bf16 v[18:21], v[164:167], v[206:209], v[18:21]
	v_mfma_f32_16x16x32_bf16 v[6:9], v[146:149], v[214:217], v[6:9]
	v_mfma_f32_16x16x32_bf16 v[2:5], v[164:167], v[214:217], v[2:5]
	v_mfma_f32_16x16x32_bf16 v[54:57], v[150:153], v[194:197], v[54:57]
	v_mfma_f32_16x16x32_bf16 v[50:53], v[180:183], v[194:197], v[50:53]
	v_mfma_f32_16x16x32_bf16 v[38:41], v[150:153], v[202:205], v[38:41]
	v_mfma_f32_16x16x32_bf16 v[34:37], v[180:183], v[202:205], v[34:37]
	v_mfma_f32_16x16x32_bf16 v[22:25], v[150:153], v[210:213], v[22:25]
	v_mfma_f32_16x16x32_bf16 v[18:21], v[180:183], v[210:213], v[18:21]
	v_mfma_f32_16x16x32_bf16 v[6:9], v[150:153], v[218:221], v[6:9]
	v_mfma_f32_16x16x32_bf16 v[2:5], v[180:183], v[218:221], v[2:5]
	s_setprio 0
	s_barrier
	s_add_u32 s44, s44, 0x100
	s_addc_u32 s45, s45, 0
	s_add_u32 s94, s94, 0x100
	s_addc_u32 s95, s95, 0
	s_cmp_ge_u32 s96, s88
	s_mov_b32 s74, s96
	s_cbranch_scc0 .LBB0_1427
	s_and_b64 vcc, exec, s[48:49]
	s_cbranch_vccz .LBB0_1430
	s_barrier

; #define PG8_STAGE(bufoff, gbase, voff) do { _Pragma("unroll") for (int _i = 0; _i < 2; ++_i) \
;         __builtin_amdgcn_global_load_lds((const unsigned*)((const char*)(gbase) + (voff)[_i]), (PG8_LAS unsigned*)(lds + (bufoff) + ldsw + _i * 8192), 16, 0, 0); } while (0)
; #define PG8_LDA(dst, b, h) do { _Pragma("unroll") for (int m = 0; m < 4; ++m) _Pragma("unroll") for (int k = 0; k < 2; ++k) dst[m][k] = *(const PG8_LAS bf16x8*)(lds + PG8_SA(b, h) + aoff + m * 2048 + k * 1024); } while (0)
; #define PG8_LDB(dst, b, h) do { _Pragma("unroll") for (int n = 0; n < 2; ++n) _Pragma("unroll") for (int k = 0; k < 2; ++k) dst[n][k] = *(const PG8_LAS bf16x8*)(lds + PG8_SB(b, h) + boff + n * 2048 + k * 1024); } while (0)
; #define PG8_MMA(ai, bj, At, Bt) do { __builtin_amdgcn_s_setprio(1); _Pragma("unroll") for (int m = 0; m < 4; ++m) _Pragma("unroll") for (int n = 0; n < 2; ++n) _Pragma("unroll") for (int k = 0; k < 2; ++k) \
;         acc[ai][bj][m][n] = __builtin_amdgcn_mfma_f32_16x16x32_bf16(Bt[n][k], At[m][k], acc[ai][bj][m][n], 0, 0, 0); __builtin_amdgcn_s_setprio(0); } while (0)
; #define PG8_WAIT_V(n) asm volatile("s_waitcnt vmcnt(" #n ")" ::: "memory")
; #define PG8_WAIT_L(n) asm volatile("s_waitcnt lgkmcnt(" #n ")" ::: "memory")
; #define PG8_BAR __builtin_amdgcn_s_barrier()
; #define PG8_SCHED __builtin_amdgcn_sched_barrier(0)
; template <class Epi, class Sched, bool ALIGN_EPI = false, bool SP2 = false>
; __device__ __forceinline__ void gemm_phase(PG8_LAS unsigned char* lds, const Gemm g, const Sched& S, const Epi& E) {
;     ...
;         for (int t = 0; t < nt; t += 2) {
;             const bool last = (t == nt - 2);
;             const char* a1 = cA + (size_t)(t + 1) * kstep;
;             const char* a2 = last ? nA : cA + (size_t)(t + 2) * kstep; const char* b2 = last ? nB : cB + (size_t)(t + 2) * kstep;
;             const char* a3 = a2 + kstep; const char* b3 = b2 + kstep;
;             if (last && has_next) S.a_ready(nxt);
;             if constexpr (SP2) {
;             PG8_LDB(B0, 0, 0); PG8_LDB(B1, 0, 1); PG8_SCHED; PG8_LDA(At, 0, 0); PG8_STAGE(PG8_SA(1, 1), a1 + hstep, voffA);
;             PG8_WAIT_V(8); PG8_WAIT_L(0); PG8_BAR; PG8_MMA(0, 0, At, B0); PG8_MMA(0, 1, At, B1); PG8_BAR; PG8_SCHED;
;             PG8_LDA(At, 0, 1); PG8_STAGE(PG8_SB(0, 0), b2, voffB); PG8_STAGE(PG8_SB(0, 1), b2 + hstep, voffB); PG8_STAGE(PG8_SA(0, 0), a2, voffA);
.LBB0_1497:
	s_add_u32 s50, s0, 0xfff80080
	s_addc_u32 s51, s1, -1
	s_add_i32 s81, 0, 0x10000
	s_cmp_eq_u32 s80, 28
	s_cselect_b32 s53, s24, s51
	s_cselect_b32 s52, s25, s50
	s_cselect_b32 s51, s43, s75
	s_cselect_b32 s50, s45, s74
	s_add_i32 s84, 0, 0x14000
	v_add_u32_e32 v152, s81, v160
	v_add_u32_e32 v156, s84, v160
	ds_read_b128 v[140:143], v152
	ds_read_b128 v[144:147], v152 offset:1024
	ds_read_b128 v[148:151], v152 offset:2048
	ds_read_b128 v[152:155], v152 offset:3072
	ds_read_b128 v[164:167], v156
	ds_read_b128 v[180:183], v156 offset:1024
	ds_read_b128 v[184:187], v156 offset:2048
	ds_read_b128 v[190:193], v156 offset:3072
	v_lshl_add_u64 v[156:157], s[0:1], 0, v[136:137]
	s_add_i32 m0, s39, 0xc000
	ds_read_b128 v[194:197], v162
	ds_read_b128 v[198:201], v162 offset:1024
	ds_read_b128 v[202:205], v162 offset:2048
	ds_read_b128 v[206:209], v162 offset:3072
	ds_read_b128 v[210:213], v162 offset:4096
	ds_read_b128 v[214:217], v162 offset:5120
	ds_read_b128 v[218:221], v162 offset:6144
	ds_read_b128 v[232:235], v162 offset:7168
	global_load_lds_dwordx4 v[156:157], off
	s_add_i32 m0, s39, 0xe000
	v_lshl_add_u64 v[156:157], s[0:1], 0, v[138:139]
	global_load_lds_dwordx4 v[156:157], off
	s_waitcnt vmcnt(8) lgkmcnt(0)
	s_setprio 1
	s_barrier
	v_mfma_f32_16x16x32_bf16 v[126:129], v[140:143], v[194:197], v[126:129]
	v_mfma_f32_16x16x32_bf16 v[122:125], v[148:151], v[194:197], v[122:125]
	v_mfma_f32_16x16x32_bf16 v[110:113], v[140:143], v[202:205], v[110:113]
	v_mfma_f32_16x16x32_bf16 v[106:109], v[148:151], v[202:205], v[106:109]
	v_mfma_f32_16x16x32_bf16 v[94:97], v[140:143], v[210:213], v[94:97]
	v_mfma_f32_16x16x32_bf16 v[90:93], v[148:151], v[210:213], v[90:93]
	v_mfma_f32_16x16x32_bf16 v[78:81], v[140:143], v[218:221], v[78:81]
	v_mfma_f32_16x16x32_bf16 v[74:77], v[148:151], v[218:221], v[74:77]
	v_mfma_f32_16x16x32_bf16 v[126:129], v[144:147], v[198:201], v[126:129]
	v_mfma_f32_16x16x32_bf16 v[122:125], v[152:155], v[198:201], v[122:125]
	v_mfma_f32_16x16x32_bf16 v[110:113], v[144:147], v[206:209], v[110:113]
	v_mfma_f32_16x16x32_bf16 v[106:109], v[152:155], v[206:209], v[106:109]
	v_mfma_f32_16x16x32_bf16 v[94:97], v[144:147], v[214:217], v[94:97]
	v_mfma_f32_16x16x32_bf16 v[90:93], v[152:155], v[214:217], v[90:93]
	v_mfma_f32_16x16x32_bf16 v[78:81], v[144:147], v[232:235], v[78:81]
	v_mfma_f32_16x16x32_bf16 v[74:77], v[152:155], v[232:235], v[74:77]
	s_setprio 0
	s_setprio 1
	v_mfma_f32_16x16x32_bf16 v[118:121], v[164:167], v[194:197], v[118:121]
	v_mfma_f32_16x16x32_bf16 v[114:117], v[184:187], v[194:197], v[114:117]
	v_mfma_f32_16x16x32_bf16 v[102:105], v[164:167], v[202:205], v[102:105]
	v_mfma_f32_16x16x32_bf16 v[98:101], v[184:187], v[202:205], v[98:101]
	v_mfma_f32_16x16x32_bf16 v[86:89], v[164:167], v[210:213], v[86:89]
	v_mfma_f32_16x16x32_bf16 v[82:85], v[184:187], v[210:213], v[82:85]
	v_mfma_f32_16x16x32_bf16 v[70:73], v[164:167], v[218:221], v[70:73]
	v_mfma_f32_16x16x32_bf16 v[66:69], v[184:187], v[218:221], v[66:69]
	v_mfma_f32_16x16x32_bf16 v[118:121], v[180:183], v[198:201], v[118:121]
	v_mfma_f32_16x16x32_bf16 v[114:117], v[190:193], v[198:201], v[114:117]
	v_mfma_f32_16x16x32_bf16 v[102:105], v[180:183], v[206:209], v[102:105]
	v_mfma_f32_16x16x32_bf16 v[98:101], v[190:193], v[206:209], v[98:101]
	v_mfma_f32_16x16x32_bf16 v[86:89], v[180:183], v[214:217], v[86:89]
	v_mfma_f32_16x16x32_bf16 v[82:85], v[190:193], v[214:217], v[82:85]
	v_mfma_f32_16x16x32_bf16 v[70:73], v[180:183], v[232:235], v[70:73]
	v_mfma_f32_16x16x32_bf16 v[66:69], v[190:193], v[232:235], v[66:69]
	s_setprio 0
	s_barrier
	s_add_i32 s81, s81, s38
	v_lshl_add_u64 v[156:157], s[50:51], 0, v[0:1]
	s_mov_b32 m0, s81
	ds_read_b128 v[194:197], v162 offset:16384
	ds_read_b128 v[198:201], v162 offset:17408
	ds_read_b128 v[202:205], v162 offset:18432
	ds_read_b128 v[206:209], v162 offset:19456
	ds_read_b128 v[210:213], v162 offset:20480
	ds_read_b128 v[214:217], v162 offset:21504
	ds_read_b128 v[218:221], v162 offset:22528
	ds_read_b128 v[232:235], v162 offset:23552
	global_load_lds_dwordx4 v[156:157], off
	s_add_i32 m0, s81, 0x2000
	s_add_u32 s82, s50, 0x80000
	v_lshl_add_u64 v[168:169], s[50:51], 0, v[130:131]
	s_addc_u32 s83, s51, 0
	s_add_i32 s81, s84, s38
	global_load_lds_dwordx4 v[168:169], off
	v_lshl_add_u64 v[222:223], s[82:83], 0, v[0:1]
	s_mov_b32 m0, s81
	v_lshl_add_u64 v[236:237], s[52:53], 0, v[132:133]
	global_load_lds_dwordx4 v[222:223], off
	s_add_i32 m0, s81, 0x2000
	v_lshl_add_u64 v[222:223], s[82:83], 0, v[130:131]
	global_load_lds_dwordx4 v[222:223], off
	s_mov_b32 m0, s39
	v_lshl_add_u64 v[222:223], s[52:53], 0, v[134:135]
	global_load_lds_dwordx4 v[222:223], off
	s_mov_b32 m0, s58
	s_nop 0
	global_load_lds_dwordx4 v[236:237], off
	s_waitcnt vmcnt(8) lgkmcnt(0)
	s_setprio 1
	s_barrier
; #define PG8_STAGE(bufoff, gbase, voff) do { _Pragma("unroll") for (int _i = 0; _i < 2; ++_i) \
;         __builtin_amdgcn_global_load_lds((const unsigned*)((const char*)(gbase) + (voff)[_i]), (PG8_LAS unsigned*)(lds + (bufoff) + ldsw + _i * 8192), 16, 0, 0); } while (0)
; #define PG8_LDA(dst, b, h) do { _Pragma("unroll") for (int m = 0; m < 4; ++m) _Pragma("unroll") for (int k = 0; k < 2; ++k) dst[m][k] = *(const PG8_LAS bf16x8*)(lds + PG8_SA(b, h) + aoff + m * 2048 + k * 1024); } while (0)
; #define PG8_LDB(dst, b, h) do { _Pragma("unroll") for (int n = 0; n < 2; ++n) _Pragma("unroll") for (int k = 0; k < 2; ++k) dst[n][k] = *(const PG8_LAS bf16x8*)(lds + PG8_SB(b, h) + boff + n * 2048 + k * 1024); } while (0)
; #define PG8_MMA(ai, bj, At, Bt) do { __builtin_amdgcn_s_setprio(1); _Pragma("unroll") for (int m = 0; m < 4; ++m) _Pragma("unroll") for (int n = 0; n < 2; ++n) _Pragma("unroll") for (int k = 0; k < 2; ++k) \
;         acc[ai][bj][m][n] = __builtin_amdgcn_mfma_f32_16x16x32_bf16(Bt[n][k], At[m][k], acc[ai][bj][m][n], 0, 0, 0); __builtin_amdgcn_s_setprio(0); } while (0)
; #define PG8_WAIT_V(n) asm volatile("s_waitcnt vmcnt(" #n ")" ::: "memory")
; #define PG8_WAIT_L(n) asm volatile("s_waitcnt lgkmcnt(" #n ")" ::: "memory")
; #define PG8_BAR __builtin_amdgcn_s_barrier()
; #define PG8_SCHED __builtin_amdgcn_sched_barrier(0)
; template <class Epi, class Sched, bool ALIGN_EPI = false, bool SP2 = false>
; __device__ __forceinline__ void gemm_phase(PG8_LAS unsigned char* lds, const Gemm g, const Sched& S, const Epi& E) {
;     ...
;             PG8_WAIT_V(8); PG8_WAIT_L(0); PG8_BAR; PG8_MMA(1, 0, At, B0); PG8_MMA(1, 1, At, B1); PG8_BAR; PG8_SCHED;
;             PG8_LDB(B0, 1, 0); PG8_LDB(B1, 1, 1); PG8_SCHED; PG8_LDA(At, 1, 0); PG8_STAGE(PG8_SA(0, 1), a2 + hstep, voffA);
;             PG8_WAIT_V(8); PG8_WAIT_L(0); PG8_BAR; PG8_MMA(0, 0, At, B0); PG8_MMA(0, 1, At, B1); PG8_BAR; PG8_SCHED;
	v_mfma_f32_16x16x32_bf16 v[62:65], v[140:143], v[194:197], v[62:65]
	v_mfma_f32_16x16x32_bf16 v[58:61], v[148:151], v[194:197], v[58:61]
	v_mfma_f32_16x16x32_bf16 v[46:49], v[140:143], v[202:205], v[46:49]
	v_mfma_f32_16x16x32_bf16 v[42:45], v[148:151], v[202:205], v[42:45]
	v_mfma_f32_16x16x32_bf16 v[30:33], v[140:143], v[210:213], v[30:33]
	v_mfma_f32_16x16x32_bf16 v[26:29], v[148:151], v[210:213], v[26:29]
	v_mfma_f32_16x16x32_bf16 v[14:17], v[140:143], v[218:221], v[14:17]
	v_mfma_f32_16x16x32_bf16 v[10:13], v[148:151], v[218:221], v[10:13]
	v_mfma_f32_16x16x32_bf16 v[62:65], v[144:147], v[198:201], v[62:65]
	v_mfma_f32_16x16x32_bf16 v[58:61], v[152:155], v[198:201], v[58:61]
	v_mfma_f32_16x16x32_bf16 v[46:49], v[144:147], v[206:209], v[46:49]
	v_mfma_f32_16x16x32_bf16 v[42:45], v[152:155], v[206:209], v[42:45]
	v_mfma_f32_16x16x32_bf16 v[30:33], v[144:147], v[214:217], v[30:33]
	v_mfma_f32_16x16x32_bf16 v[26:29], v[152:155], v[214:217], v[26:29]
	v_mfma_f32_16x16x32_bf16 v[14:17], v[144:147], v[232:235], v[14:17]
	v_mfma_f32_16x16x32_bf16 v[10:13], v[152:155], v[232:235], v[10:13]
	s_setprio 0
	s_setprio 1
	v_mfma_f32_16x16x32_bf16 v[54:57], v[164:167], v[194:197], v[54:57]
	v_mfma_f32_16x16x32_bf16 v[50:53], v[184:187], v[194:197], v[50:53]
	v_mfma_f32_16x16x32_bf16 v[38:41], v[164:167], v[202:205], v[38:41]
	v_mfma_f32_16x16x32_bf16 v[34:37], v[184:187], v[202:205], v[34:37]
	v_mfma_f32_16x16x32_bf16 v[22:25], v[164:167], v[210:213], v[22:25]
	v_mfma_f32_16x16x32_bf16 v[18:21], v[184:187], v[210:213], v[18:21]
	v_mfma_f32_16x16x32_bf16 v[6:9], v[164:167], v[218:221], v[6:9]
	v_mfma_f32_16x16x32_bf16 v[2:5], v[184:187], v[218:221], v[2:5]
	v_mfma_f32_16x16x32_bf16 v[54:57], v[180:183], v[198:201], v[54:57]
	v_mfma_f32_16x16x32_bf16 v[50:53], v[190:193], v[198:201], v[50:53]
	v_mfma_f32_16x16x32_bf16 v[38:41], v[180:183], v[206:209], v[38:41]
	v_mfma_f32_16x16x32_bf16 v[34:37], v[190:193], v[206:209], v[34:37]
	v_mfma_f32_16x16x32_bf16 v[22:25], v[180:183], v[214:217], v[22:25]
	v_mfma_f32_16x16x32_bf16 v[18:21], v[190:193], v[214:217], v[18:21]
	v_mfma_f32_16x16x32_bf16 v[6:9], v[180:183], v[232:235], v[6:9]
	v_mfma_f32_16x16x32_bf16 v[2:5], v[190:193], v[232:235], v[2:5]
	s_setprio 0
	s_barrier
	s_add_i32 s81, 0, 0x18000
	s_add_i32 s82, 0, 0x1c000
	v_add_u32_e32 v152, s81, v160
	v_add_u32_e32 v158, s82, v160
	ds_read_b128 v[140:143], v152
	ds_read_b128 v[144:147], v152 offset:1024
	ds_read_b128 v[148:151], v152 offset:2048
	ds_read_b128 v[152:155], v152 offset:3072
	ds_read_b128 v[164:167], v158
	ds_read_b128 v[180:183], v158 offset:1024
	ds_read_b128 v[184:187], v158 offset:2048
	ds_read_b128 v[190:193], v158 offset:3072
	s_add_u32 s52, s52, 0x80000
	s_addc_u32 s53, s53, 0
	s_mov_b32 m0, s60
	v_lshl_add_u64 v[238:239], s[52:53], 0, v[134:135]
	ds_read_b128 v[194:197], v162 offset:32768
	ds_read_b128 v[198:201], v162 offset:33792
	ds_read_b128 v[202:205], v162 offset:34816
	ds_read_b128 v[206:209], v162 offset:35840
	ds_read_b128 v[210:213], v162 offset:36864
	ds_read_b128 v[214:217], v162 offset:37888
	ds_read_b128 v[218:221], v162 offset:38912
	ds_read_b128 v[232:235], v162 offset:39936
	global_load_lds_dwordx4 v[238:239], off
	s_mov_b32 m0, s61
	v_lshl_add_u64 v[238:239], s[52:53], 0, v[132:133]
	global_load_lds_dwordx4 v[238:239], off
	s_waitcnt vmcnt(8) lgkmcnt(0)
	s_setprio 1
	s_barrier
	v_mfma_f32_16x16x32_bf16 v[126:129], v[140:143], v[194:197], v[126:129]
	v_mfma_f32_16x16x32_bf16 v[122:125], v[148:151], v[194:197], v[122:125]
	v_mfma_f32_16x16x32_bf16 v[110:113], v[140:143], v[202:205], v[110:113]
	v_mfma_f32_16x16x32_bf16 v[106:109], v[148:151], v[202:205], v[106:109]
	v_mfma_f32_16x16x32_bf16 v[94:97], v[140:143], v[210:213], v[94:97]
	v_mfma_f32_16x16x32_bf16 v[90:93], v[148:151], v[210:213], v[90:93]
	v_mfma_f32_16x16x32_bf16 v[78:81], v[140:143], v[218:221], v[78:81]
	v_mfma_f32_16x16x32_bf16 v[74:77], v[148:151], v[218:221], v[74:77]
	v_mfma_f32_16x16x32_bf16 v[126:129], v[144:147], v[198:201], v[126:129]
	v_mfma_f32_16x16x32_bf16 v[122:125], v[152:155], v[198:201], v[122:125]
	v_mfma_f32_16x16x32_bf16 v[110:113], v[144:147], v[206:209], v[110:113]
	v_mfma_f32_16x16x32_bf16 v[106:109], v[152:155], v[206:209], v[106:109]
	v_mfma_f32_16x16x32_bf16 v[94:97], v[144:147], v[214:217], v[94:97]
	v_mfma_f32_16x16x32_bf16 v[90:93], v[152:155], v[214:217], v[90:93]
	v_mfma_f32_16x16x32_bf16 v[78:81], v[144:147], v[232:235], v[78:81]
	v_mfma_f32_16x16x32_bf16 v[74:77], v[152:155], v[232:235], v[74:77]
	s_setprio 0
	s_setprio 1
	v_mfma_f32_16x16x32_bf16 v[118:121], v[164:167], v[194:197], v[118:121]
	v_mfma_f32_16x16x32_bf16 v[114:117], v[184:187], v[194:197], v[114:117]
	v_mfma_f32_16x16x32_bf16 v[102:105], v[164:167], v[202:205], v[102:105]
	v_mfma_f32_16x16x32_bf16 v[98:101], v[184:187], v[202:205], v[98:101]
	v_mfma_f32_16x16x32_bf16 v[86:89], v[164:167], v[210:213], v[86:89]
	v_mfma_f32_16x16x32_bf16 v[82:85], v[184:187], v[210:213], v[82:85]
	v_mfma_f32_16x16x32_bf16 v[70:73], v[164:167], v[218:221], v[70:73]
	v_mfma_f32_16x16x32_bf16 v[66:69], v[184:187], v[218:221], v[66:69]
	v_mfma_f32_16x16x32_bf16 v[118:121], v[180:183], v[198:201], v[118:121]
	v_mfma_f32_16x16x32_bf16 v[114:117], v[190:193], v[198:201], v[114:117]
	v_mfma_f32_16x16x32_bf16 v[102:105], v[180:183], v[206:209], v[102:105]
	v_mfma_f32_16x16x32_bf16 v[98:101], v[190:193], v[206:209], v[98:101]
	v_mfma_f32_16x16x32_bf16 v[86:89], v[180:183], v[214:217], v[86:89]
	v_mfma_f32_16x16x32_bf16 v[82:85], v[190:193], v[214:217], v[82:85]
	v_mfma_f32_16x16x32_bf16 v[70:73], v[180:183], v[232:235], v[70:73]
	v_mfma_f32_16x16x32_bf16 v[66:69], v[190:193], v[232:235], v[66:69]
	s_setprio 0
	s_barrier
; #define PG8_STAGE(bufoff, gbase, voff) do { _Pragma("unroll") for (int _i = 0; _i < 2; ++_i) \
;         __builtin_amdgcn_global_load_lds((const unsigned*)((const char*)(gbase) + (voff)[_i]), (PG8_LAS unsigned*)(lds + (bufoff) + ldsw + _i * 8192), 16, 0, 0); } while (0)
; #define PG8_LDA(dst, b, h) do { _Pragma("unroll") for (int m = 0; m < 4; ++m) _Pragma("unroll") for (int k = 0; k < 2; ++k) dst[m][k] = *(const PG8_LAS bf16x8*)(lds + PG8_SA(b, h) + aoff + m * 2048 + k * 1024); } while (0)
; #define PG8_MMA(ai, bj, At, Bt) do { __builtin_amdgcn_s_setprio(1); _Pragma("unroll") for (int m = 0; m < 4; ++m) _Pragma("unroll") for (int n = 0; n < 2; ++n) _Pragma("unroll") for (int k = 0; k < 2; ++k) \
;         acc[ai][bj][m][n] = __builtin_amdgcn_mfma_f32_16x16x32_bf16(Bt[n][k], At[m][k], acc[ai][bj][m][n], 0, 0, 0); __builtin_amdgcn_s_setprio(0); } while (0)
; #define PG8_WAIT_V(n) asm volatile("s_waitcnt vmcnt(" #n ")" ::: "memory")
; #define PG8_WAIT_L(n) asm volatile("s_waitcnt lgkmcnt(" #n ")" ::: "memory")
; #define PG8_BAR __builtin_amdgcn_s_barrier()
; #define PG8_SCHED __builtin_amdgcn_sched_barrier(0)
; template <class Epi, class Sched, bool ALIGN_EPI = false, bool SP2 = false>
; __device__ __forceinline__ void gemm_phase(PG8_LAS unsigned char* lds, const Gemm g, const Sched& S, const Epi& E) {
;     ...
;             PG8_LDA(At, 1, 1); PG8_STAGE(PG8_SB(1, 0), b3, voffB); PG8_STAGE(PG8_SB(1, 1), b3 + hstep, voffB); PG8_STAGE(PG8_SA(1, 0), a3, voffA);
;             PG8_WAIT_V(8); PG8_WAIT_L(0); PG8_BAR; PG8_MMA(1, 0, At, B0); PG8_MMA(1, 1, At, B1); PG8_BAR; PG8_SCHED;
;     ...
;         }
;         if constexpr (ALIGN_EPI) { if (wr == 0) PG8_BAR; }
	s_add_i32 s52, s81, s38
	v_lshl_add_u64 v[156:157], v[156:157], 0, s[12:13]
	s_mov_b32 m0, s52
	ds_read_b128 v[194:197], v162 offset:49152
	ds_read_b128 v[198:201], v162 offset:50176
	ds_read_b128 v[202:205], v162 offset:51200
	ds_read_b128 v[206:209], v162 offset:52224
	ds_read_b128 v[210:213], v162 offset:53248
	ds_read_b128 v[214:217], v162 offset:54272
	ds_read_b128 v[218:221], v162 offset:55296
	ds_read_b128 v[232:235], v162 offset:56320
	global_load_lds_dwordx4 v[156:157], off
	s_add_i32 m0, s52, 0x2000
	s_add_u32 s50, s50, 0x80080
	v_lshl_add_u64 v[156:157], v[168:169], 0, s[12:13]
	s_addc_u32 s51, s51, 0
	s_add_i32 s52, s82, s38
	global_load_lds_dwordx4 v[156:157], off
	s_mov_b32 m0, s52
	v_lshl_add_u64 v[156:157], s[50:51], 0, v[0:1]
	global_load_lds_dwordx4 v[156:157], off
	s_add_i32 m0, s52, 0x2000
	v_lshl_add_u64 v[156:157], s[50:51], 0, v[130:131]
	global_load_lds_dwordx4 v[156:157], off
	s_mov_b32 m0, s62
	v_lshl_add_u64 v[156:157], v[222:223], 0, s[12:13]
	global_load_lds_dwordx4 v[156:157], off
	s_mov_b32 m0, s63
	v_lshl_add_u64 v[156:157], v[236:237], 0, s[12:13]
	global_load_lds_dwordx4 v[156:157], off
	s_waitcnt vmcnt(8) lgkmcnt(0)
	s_setprio 1
	s_barrier
	v_mfma_f32_16x16x32_bf16 v[62:65], v[140:143], v[194:197], v[62:65]
	v_mfma_f32_16x16x32_bf16 v[58:61], v[148:151], v[194:197], v[58:61]
	v_mfma_f32_16x16x32_bf16 v[46:49], v[140:143], v[202:205], v[46:49]
	v_mfma_f32_16x16x32_bf16 v[42:45], v[148:151], v[202:205], v[42:45]
	v_mfma_f32_16x16x32_bf16 v[30:33], v[140:143], v[210:213], v[30:33]
	v_mfma_f32_16x16x32_bf16 v[26:29], v[148:151], v[210:213], v[26:29]
	v_mfma_f32_16x16x32_bf16 v[14:17], v[140:143], v[218:221], v[14:17]
	v_mfma_f32_16x16x32_bf16 v[10:13], v[148:151], v[218:221], v[10:13]
	v_mfma_f32_16x16x32_bf16 v[62:65], v[144:147], v[198:201], v[62:65]
	v_mfma_f32_16x16x32_bf16 v[58:61], v[152:155], v[198:201], v[58:61]
	v_mfma_f32_16x16x32_bf16 v[46:49], v[144:147], v[206:209], v[46:49]
	v_mfma_f32_16x16x32_bf16 v[42:45], v[152:155], v[206:209], v[42:45]
	v_mfma_f32_16x16x32_bf16 v[30:33], v[144:147], v[214:217], v[30:33]
	v_mfma_f32_16x16x32_bf16 v[26:29], v[152:155], v[214:217], v[26:29]
	v_mfma_f32_16x16x32_bf16 v[14:17], v[144:147], v[232:235], v[14:17]
	v_mfma_f32_16x16x32_bf16 v[10:13], v[152:155], v[232:235], v[10:13]
	s_setprio 0
	s_setprio 1
	v_mfma_f32_16x16x32_bf16 v[54:57], v[164:167], v[194:197], v[54:57]
	v_mfma_f32_16x16x32_bf16 v[50:53], v[184:187], v[194:197], v[50:53]
	v_mfma_f32_16x16x32_bf16 v[38:41], v[164:167], v[202:205], v[38:41]
	v_mfma_f32_16x16x32_bf16 v[34:37], v[184:187], v[202:205], v[34:37]
	v_mfma_f32_16x16x32_bf16 v[22:25], v[164:167], v[210:213], v[22:25]
	v_mfma_f32_16x16x32_bf16 v[18:21], v[184:187], v[210:213], v[18:21]
	v_mfma_f32_16x16x32_bf16 v[6:9], v[164:167], v[218:221], v[6:9]
	v_mfma_f32_16x16x32_bf16 v[2:5], v[184:187], v[218:221], v[2:5]
	v_mfma_f32_16x16x32_bf16 v[54:57], v[180:183], v[198:201], v[54:57]
	v_mfma_f32_16x16x32_bf16 v[50:53], v[190:193], v[198:201], v[50:53]
	v_mfma_f32_16x16x32_bf16 v[38:41], v[180:183], v[206:209], v[38:41]
	v_mfma_f32_16x16x32_bf16 v[34:37], v[190:193], v[206:209], v[34:37]
	v_mfma_f32_16x16x32_bf16 v[22:25], v[180:183], v[214:217], v[22:25]
	v_mfma_f32_16x16x32_bf16 v[18:21], v[190:193], v[214:217], v[18:21]
	v_mfma_f32_16x16x32_bf16 v[6:9], v[180:183], v[232:235], v[6:9]
	v_mfma_f32_16x16x32_bf16 v[2:5], v[190:193], v[232:235], v[2:5]
	s_setprio 0
	s_barrier
	s_add_i32 s80, s80, 2
	s_add_u32 s0, s0, 0x100
	s_addc_u32 s1, s1, 0
	s_add_u32 s74, s74, 0x100
	s_addc_u32 s75, s75, 0
	s_cmp_gt_u32 s80, 29
	s_cbranch_scc0 .LBB0_1497
	s_and_b64 vcc, exec, s[30:31]
	s_cbranch_vccz .LBB0_1500
	s_barrier
